# strategy 4 A/B: static s_setprio 1 for waves 0-3 (older half) during attention instead of waves 4-7
# speedup vs baseline: 1.0069x; 1.0017x over previous
; #define LAS __attribute__((address_space(3)))
; __device__ __forceinline__ void xcd_barrier(const XcdBarrier& b) {
;     ...
;     }
;     __syncthreads();
; }
; __global__ void __launch_bounds__(512, 2) fwd(Args a) {
;     ...
;         if (IN(p0 + 4)) { att::attn_phase(a, l, (LAS char*)lds, 0); }
.LBB0_435:
	s_or_b64 exec, exec, s[0:1]
	v_readlane_b32 s16, v252, 18
	v_readlane_b32 s22, v252, 24
	v_readlane_b32 s23, v252, 25
	s_waitcnt lgkmcnt(0)
	s_barrier
	v_readfirstlane_b32 s100, v236
	s_lshr_b32 s100, s100, 6
	s_cmp_ge_u32 s100, 4
	s_cbranch_scc1 .Latt_prio_skip
	s_setprio 1
